# bf16 in-proj round 2: workgroup groups swap column tiles so each workgroup gets one silu-epilogue tile and one plain tile (was two of a kind); evens out the in-proj phase before its grid barrier
# baseline (speedup 1.0000x reference)
.LBB0_644:
	s_mov_b32 s8, s86
	s_add_i32 s86, s86, 1
	s_cmp_gt_u32 s8, 0xffffe
	s_mov_b64 s[30:31], 0
	s_cbranch_scc1 .LBB0_651
	s_mul_i32 s8, s86, s95
	s_mul_hi_u32 s9, s86, s26
	s_add_i32 s9, s9, s8
	s_mul_i32 s8, s86, s26
	s_add_u32 s34, s8, s64
	s_addc_u32 s35, s9, s7
	s_cmp_eq_u32 s86, 2
	s_cselect_b32 s8, 0x80, 0
	s_xor_b32 s34, s34, s8
	v_mov_b64_e32 v[0:1], 0x3ff
	v_cmp_gt_i64_e32 vcc, s[34:35], v[0:1]
	s_cbranch_vccnz .LBB0_651
	s_ashr_i32 s8, s34, 31
	s_lshr_b32 s8, s8, 29
	s_add_i32 s8, s34, s8
	s_and_b32 s9, s8, -8
	s_sub_i32 s9, s34, s9
	s_cmp_gt_i32 s9, -1
	s_mov_b64 s[18:19], -1
	s_cbranch_scc0 .LBB0_648
	s_lshl_b32 s20, s9, 7
	s_mov_b64 s[18:19], 0
